# v28 + grid barrier: non-leader workgroups poll the cross-XCD release word directly instead of the per-XCD one
# speedup vs baseline: 1.0005x; 1.0005x over previous
.LBB0_536:
	v_readlane_b32 s4, v253, 48
	v_readlane_b32 s5, v253, 49
	v_cvt_f32_u32_e32 v1, v2
	v_sub_u32_e32 v4, 0, v2
	v_rcp_iflag_f32_e32 v1, v1
	s_nop 1
	global_atomic_add v3, v64, v216, s[4:5] sc0
	buffer_inv sc1
	v_mul_f32_e32 v1, 0x4f7ffffe, v1
	v_cvt_u32_f32_e32 v1, v1
	v_mul_lo_u32 v4, v4, v1
	v_mul_hi_u32 v4, v1, v4
	v_add_u32_e32 v1, v1, v4
	s_waitcnt vmcnt(1)
	v_mul_hi_u32 v1, v3, v1
	v_mul_lo_u32 v4, v1, v2
	v_sub_u32_e32 v4, v3, v4
	v_add_u32_e32 v5, 1, v1
	v_cmp_ge_u32_e32 vcc, v4, v2
	v_add_u32_e32 v3, 1, v3
	s_nop 0
	v_cndmask_b32_e32 v1, v1, v5, vcc
	v_sub_u32_e32 v5, v4, v2
	v_cndmask_b32_e32 v4, v4, v5, vcc
	v_add_u32_e32 v5, 1, v1
	v_cmp_ge_u32_e32 vcc, v4, v2
	s_nop 1
	v_cndmask_b32_e32 v1, v1, v5, vcc
	v_mul_lo_u32 v4, v2, v1
	v_add_u32_e32 v2, v4, v2
	v_cmp_ne_u32_e32 vcc, v3, v2
	s_and_saveexec_b64 s[4:5], vcc
	s_xor_b64 s[4:5], exec, s[4:5]
	s_cbranch_execz .LBB0_550
	v_readlane_b32 s6, v253, 54
	v_readlane_b32 s7, v253, 55
	s_waitcnt lgkmcnt(0)
	s_nop 3
	global_load_dword v0, v64, s[6:7] sc1
	s_waitcnt vmcnt(0)
	v_cmp_eq_u32_e32 vcc, v0, v1
	s_and_saveexec_b64 s[6:7], vcc
	s_cbranch_execz .LBB0_549
	s_mov_b32 s12, 1
	s_mov_b64 s[8:9], 0
	s_branch .LBB0_540

.LBB0_544:
	v_readlane_b32 s14, v253, 54
	v_readlane_b32 s15, v253, 55
	s_add_i32 s12, s12, 1
	s_mov_b64 s[18:19], -1
	s_nop 2
	global_load_dword v0, v64, s[14:15] sc1
	s_waitcnt vmcnt(0)
	v_cmp_ne_u32_e32 vcc, v0, v1
	s_orn2_b64 s[16:17], vcc, exec
	s_branch .LBB0_539

.LBB0_616:
	v_readlane_b32 s4, v253, 48
	v_readlane_b32 s5, v253, 49
	v_cvt_f32_u32_e32 v1, v2
	v_sub_u32_e32 v4, 0, v2
	v_rcp_iflag_f32_e32 v1, v1
	s_nop 1
	global_atomic_add v3, v64, v216, s[4:5] sc0
	buffer_inv sc1
	v_mul_f32_e32 v1, 0x4f7ffffe, v1
	v_cvt_u32_f32_e32 v1, v1
	v_mul_lo_u32 v4, v4, v1
	v_mul_hi_u32 v4, v1, v4
	v_add_u32_e32 v1, v1, v4
	s_waitcnt vmcnt(1)
	v_mul_hi_u32 v1, v3, v1
	v_mul_lo_u32 v4, v1, v2
	v_sub_u32_e32 v4, v3, v4
	v_add_u32_e32 v5, 1, v1
	v_cmp_ge_u32_e32 vcc, v4, v2
	v_add_u32_e32 v3, 1, v3
	s_nop 0
	v_cndmask_b32_e32 v1, v1, v5, vcc
	v_sub_u32_e32 v5, v4, v2
	v_cndmask_b32_e32 v4, v4, v5, vcc
	v_add_u32_e32 v5, 1, v1
	v_cmp_ge_u32_e32 vcc, v4, v2
	s_nop 1
	v_cndmask_b32_e32 v1, v1, v5, vcc
	v_mul_lo_u32 v4, v2, v1
	v_add_u32_e32 v2, v4, v2
	v_cmp_ne_u32_e32 vcc, v3, v2
	s_and_saveexec_b64 s[4:5], vcc
	s_xor_b64 s[4:5], exec, s[4:5]
	s_cbranch_execz .LBB0_630
	v_readlane_b32 s6, v253, 54
	v_readlane_b32 s7, v253, 55
	s_waitcnt lgkmcnt(0)
	s_nop 3
	global_load_dword v0, v64, s[6:7] sc1
	s_waitcnt vmcnt(0)
	v_cmp_eq_u32_e32 vcc, v0, v1
	s_and_saveexec_b64 s[6:7], vcc
	s_cbranch_execz .LBB0_629
	s_mov_b32 s13, 1
	s_mov_b64 s[8:9], 0
	s_branch .LBB0_620

.LBB0_624:
	v_readlane_b32 s14, v253, 54
	v_readlane_b32 s15, v253, 55
	s_add_i32 s13, s13, 1
	s_mov_b64 s[18:19], -1
	s_nop 2
	global_load_dword v0, v64, s[14:15] sc1
	s_waitcnt vmcnt(0)
	v_cmp_ne_u32_e32 vcc, v0, v1
	s_orn2_b64 s[16:17], vcc, exec
	s_branch .LBB0_619
